# first grid barrier: the 16 census counter loads issued together and waited once (were 15 serial round trips)
# baseline (speedup 1.0000x reference)
; __device__ __forceinline__ unsigned xb_ld(unsigned* p)              { return __hip_atomic_load(p, __ATOMIC_RELAXED, __HIP_MEMORY_SCOPE_AGENT); }
; __device__ __forceinline__ void xcd_barrier_complete(unsigned* bar, unsigned x, unsigned& nloc, unsigned& nx) {
;     ...
;     for (;;) {
;         sum = 0u; cnt = 0u; mine = 0u;
; #pragma unroll
;         for (unsigned j = 0; j < 16; ++j) { const unsigned c = xb_ld(&bar[XB_XCNT(j)]); sum += c; cnt += (c > 0u) ? 1u : 0u; mine = (j == x) ? c : mine; }
;         if (sum == G) break;
;         __builtin_amdgcn_s_sleep(1);
;         if ((++sp & 255u) == 0u) { if (xb_ld(&bar[XB_TMO])) break; if (sp > XB_SPIN_CAP) { atomicAdd(&bar[XB_TMO], 1u); break; } }
;     }
.LBB0_125:
	s_mov_b64 s[6:7], -1
	v_readlane_b32 s2, v252, 11
	v_readlane_b32 s3, v252, 12
	s_nop 4
	global_load_dword v0, v129, s[2:3] sc1
	v_readlane_b32 s2, v252, 13
	v_readlane_b32 s3, v252, 14
	s_nop 4
	global_load_dword v1, v129, s[2:3] sc1
	v_readlane_b32 s2, v252, 15
	v_readlane_b32 s3, v252, 16
	s_nop 4
	global_load_dword v2, v129, s[2:3] sc1
	v_readlane_b32 s2, v252, 17
	v_readlane_b32 s3, v252, 18
	s_nop 4
	global_load_dword v3, v129, s[2:3] sc1
	v_readlane_b32 s2, v252, 19
	v_readlane_b32 s3, v252, 20
	s_nop 4
	global_load_dword v4, v129, s[2:3] sc1
	v_readlane_b32 s2, v252, 21
	v_readlane_b32 s3, v252, 22
	s_nop 4
	global_load_dword v5, v129, s[2:3] sc1
	v_readlane_b32 s2, v252, 23
	v_readlane_b32 s3, v252, 24
	s_nop 4
	global_load_dword v6, v129, s[2:3] sc1
	v_readlane_b32 s2, v252, 25
	v_readlane_b32 s3, v252, 26
	s_nop 4
	global_load_dword v7, v129, s[2:3] sc1
	v_readlane_b32 s2, v252, 27
	v_readlane_b32 s3, v252, 28
	s_nop 4
	global_load_dword v8, v129, s[2:3] sc1
	v_readlane_b32 s2, v252, 29
	v_readlane_b32 s3, v252, 30
	s_nop 4
	global_load_dword v9, v129, s[2:3] sc1
	v_readlane_b32 s2, v252, 31
	v_readlane_b32 s3, v252, 32
	s_nop 4
	global_load_dword v10, v129, s[2:3] sc1
	v_readlane_b32 s2, v252, 33
	v_readlane_b32 s3, v252, 34
	s_nop 4
	global_load_dword v11, v129, s[2:3] sc1
	v_readlane_b32 s2, v252, 35
	v_readlane_b32 s3, v252, 36
	s_nop 4
	global_load_dword v12, v129, s[2:3] sc1
	v_readlane_b32 s2, v252, 37
	v_readlane_b32 s3, v252, 38
	s_nop 4
	global_load_dword v13, v129, s[2:3] sc1
	v_readlane_b32 s2, v252, 39
	v_readlane_b32 s3, v252, 40
	s_nop 4
	global_load_dword v14, v129, s[2:3] sc1
	v_readlane_b32 s2, v252, 41
	v_readlane_b32 s3, v252, 42
	s_nop 4
	global_load_dword v15, v129, s[2:3] sc1
	s_mov_b64 s[2:3], -1
	s_waitcnt vmcnt(0)
	v_add_u32_e32 v16, v1, v0
	v_add_u32_e32 v16, v16, v2
	v_add_u32_e32 v16, v16, v3
	v_add_u32_e32 v16, v16, v4
	v_add_u32_e32 v16, v16, v5
	v_add_u32_e32 v16, v16, v6
	v_add_u32_e32 v16, v16, v7
	v_add_u32_e32 v16, v16, v8
	v_add_u32_e32 v16, v16, v9
	v_add_u32_e32 v16, v16, v10
	v_add_u32_e32 v16, v16, v11
	v_add_u32_e32 v16, v16, v12
	v_add_u32_e32 v16, v16, v13
	v_add_u32_e32 v16, v16, v14
	v_add_u32_e32 v16, v16, v15
	v_cmp_eq_u32_e32 vcc, s10, v16
	s_cbranch_vccnz .LBB0_124
	s_and_b32 s2, s11, 0xff
	s_cmp_eq_u32 s2, 0
	s_mov_b64 s[2:3], -1
	s_mov_b64 s[8:9], -1
	s_sleep 1
	s_cbranch_scc0 .LBB0_129
	v_readlane_b32 s2, v252, 9
	v_readlane_b32 s3, v252, 10
	s_nop 4
	global_load_dword v16, v129, s[2:3] sc1
	s_waitcnt vmcnt(0)
	v_cmp_eq_u32_e32 vcc, 0, v16
	s_cbranch_vccnz .LBB0_131
	s_mov_b64 s[8:9], 0
	s_mov_b64 s[2:3], -1
